# dma+cvt2 + sc1 write-through policy on P1, P3(merged) and P4(out) epilogue stores
# baseline (speedup 1.0000x reference)
.LBB0_502:
	global_load_dwordx4 v[160:163], v[214:215], off offset:256
	v_add_co_u32_e32 v130, vcc, 0x90000, v214
	v_ashrrev_i32_e32 v157, 31, v156
	s_nop 0
	v_addc_co_u32_e32 v131, vcc, 0, v215, vcc
	global_load_dwordx4 v[150:153], v[130:131], off
	global_load_dwordx4 v[146:149], v[130:131], off offset:256
	v_add_co_u32_e32 v130, vcc, 0x120000, v214
	v_pk_mul_f32 v[164:165], v[126:127], v[192:193]
	s_nop 0
	v_addc_co_u32_e32 v131, vcc, 0, v215, vcc
	global_load_dwordx4 v[142:145], v[130:131], off
	global_load_dwordx4 v[138:141], v[130:131], off offset:256
	v_add_co_u32_e32 v130, vcc, 0x1b0000, v214
	v_pk_mul_f32 v[166:167], v[128:129], v[190:191]
	s_nop 0
	v_addc_co_u32_e32 v131, vcc, 0, v215, vcc
	global_load_dwordx4 v[134:137], v[130:131], off
	s_nop 0
	global_load_dwordx4 v[130:133], v[130:131], off offset:256
	v_lshlrev_b64 v[158:159], 12, v[156:157]
	v_cvt_pk_bf16_f32 v164, v164, v165
	v_cvt_pk_bf16_f32 v165, v166, v167
	v_pk_mul_f32 v[166:167], v[122:123], v[188:189]
	v_pk_mul_f32 v[168:169], v[124:125], v[186:187]
	v_cvt_pk_bf16_f32 v166, v166, v167
	v_cvt_pk_bf16_f32 v167, v168, v169
	v_lshl_add_u64 v[168:169], s[12:13], 0, v[158:159]
	v_lshlrev_b64 v[158:159], 1, v[154:155]
	v_lshl_add_u64 v[154:155], v[168:169], 0, v[158:159]
	global_store_dwordx4 v[154:155], v[164:167], off sc1
	s_mov_b32 s0, 0x480000
	s_waitcnt vmcnt(7)
	v_lshlrev_b32_e32 v164, 16, v160
	v_and_b32_e32 v165, 0xffff0000, v160
	v_pk_mul_f32 v[164:165], v[94:95], v[164:165]
	s_nop 0
	v_cvt_pk_bf16_f32 v160, v164, v165
	v_lshlrev_b32_e32 v164, 16, v161
	v_and_b32_e32 v165, 0xffff0000, v161
	v_pk_mul_f32 v[164:165], v[96:97], v[164:165]
	s_nop 0
	v_cvt_pk_bf16_f32 v161, v164, v165
	v_lshlrev_b32_e32 v164, 16, v162
	v_and_b32_e32 v165, 0xffff0000, v162
	v_pk_mul_f32 v[164:165], v[90:91], v[164:165]
	s_nop 0
	v_cvt_pk_bf16_f32 v162, v164, v165
	v_lshlrev_b32_e32 v164, 16, v163
	v_and_b32_e32 v165, 0xffff0000, v163
	v_pk_mul_f32 v[164:165], v[92:93], v[164:165]
	s_nop 0
	v_cvt_pk_bf16_f32 v163, v164, v165
	global_store_dwordx4 v[154:155], v[160:163], off offset:256 sc1
	s_waitcnt vmcnt(7)
	s_nop 0
	v_lshlrev_b32_e32 v162, 16, v150
	v_and_b32_e32 v163, 0xffff0000, v150
	v_pk_mul_f32 v[162:163], v[118:119], v[162:163]
	v_or_b32_e32 v160, 16, v156
	v_cvt_pk_bf16_f32 v150, v162, v163
	v_lshlrev_b32_e32 v162, 16, v151
	v_and_b32_e32 v163, 0xffff0000, v151
	v_pk_mul_f32 v[162:163], v[120:121], v[162:163]
	v_ashrrev_i32_e32 v161, 31, v160
	v_cvt_pk_bf16_f32 v151, v162, v163
	v_lshlrev_b32_e32 v162, 16, v152
	v_and_b32_e32 v163, 0xffff0000, v152
	v_pk_mul_f32 v[162:163], v[114:115], v[162:163]
	v_lshlrev_b64 v[160:161], 12, v[160:161]
	v_cvt_pk_bf16_f32 v152, v162, v163
	v_lshlrev_b32_e32 v162, 16, v153
	v_and_b32_e32 v163, 0xffff0000, v153
	v_pk_mul_f32 v[162:163], v[116:117], v[162:163]
	v_lshl_add_u64 v[160:161], s[12:13], 0, v[160:161]
	v_cvt_pk_bf16_f32 v153, v162, v163
	v_lshl_add_u64 v[160:161], v[160:161], 0, v[158:159]
	global_store_dwordx4 v[160:161], v[150:153], off sc1
	s_waitcnt vmcnt(7)
	s_nop 0
	v_lshlrev_b32_e32 v150, 16, v146
	v_and_b32_e32 v151, 0xffff0000, v146
	v_pk_mul_f32 v[150:151], v[86:87], v[150:151]
	s_nop 0
	v_cvt_pk_bf16_f32 v146, v150, v151
	v_lshlrev_b32_e32 v150, 16, v147
	v_and_b32_e32 v151, 0xffff0000, v147
	v_pk_mul_f32 v[150:151], v[88:89], v[150:151]
	s_nop 0
	v_cvt_pk_bf16_f32 v147, v150, v151
	v_lshlrev_b32_e32 v150, 16, v148
	v_and_b32_e32 v151, 0xffff0000, v148
	v_pk_mul_f32 v[150:151], v[82:83], v[150:151]
	s_nop 0
	v_cvt_pk_bf16_f32 v148, v150, v151
	v_lshlrev_b32_e32 v150, 16, v149
	v_and_b32_e32 v151, 0xffff0000, v149
	v_pk_mul_f32 v[150:151], v[84:85], v[150:151]
	s_nop 0
	v_cvt_pk_bf16_f32 v149, v150, v151
	global_store_dwordx4 v[160:161], v[146:149], off offset:256 sc1
	s_waitcnt vmcnt(7)
	s_nop 0
	v_lshlrev_b32_e32 v148, 16, v142
	v_and_b32_e32 v149, 0xffff0000, v142
	v_pk_mul_f32 v[148:149], v[110:111], v[148:149]
	v_or_b32_e32 v146, 32, v156
	v_cvt_pk_bf16_f32 v142, v148, v149
	v_lshlrev_b32_e32 v148, 16, v143
	v_and_b32_e32 v149, 0xffff0000, v143
	v_pk_mul_f32 v[148:149], v[112:113], v[148:149]
	v_ashrrev_i32_e32 v147, 31, v146
	v_cvt_pk_bf16_f32 v143, v148, v149
	v_lshlrev_b32_e32 v148, 16, v144
	v_and_b32_e32 v149, 0xffff0000, v144
	v_pk_mul_f32 v[148:149], v[106:107], v[148:149]
	v_lshlrev_b64 v[146:147], 12, v[146:147]
	v_cvt_pk_bf16_f32 v144, v148, v149
	v_lshlrev_b32_e32 v148, 16, v145
	v_and_b32_e32 v149, 0xffff0000, v145
	v_pk_mul_f32 v[148:149], v[108:109], v[148:149]
	v_lshl_add_u64 v[146:147], s[12:13], 0, v[146:147]
	v_cvt_pk_bf16_f32 v145, v148, v149
	v_lshl_add_u64 v[146:147], v[146:147], 0, v[158:159]
	global_store_dwordx4 v[146:147], v[142:145], off sc1
	s_waitcnt vmcnt(7)
	s_nop 0
	v_lshlrev_b32_e32 v142, 16, v138
	v_and_b32_e32 v143, 0xffff0000, v138
	v_pk_mul_f32 v[142:143], v[78:79], v[142:143]
	s_nop 0
	v_cvt_pk_bf16_f32 v138, v142, v143
	v_lshlrev_b32_e32 v142, 16, v139
	v_and_b32_e32 v143, 0xffff0000, v139
	v_pk_mul_f32 v[142:143], v[80:81], v[142:143]
	s_nop 0
	v_cvt_pk_bf16_f32 v139, v142, v143
	v_lshlrev_b32_e32 v142, 16, v140
	v_and_b32_e32 v143, 0xffff0000, v140
	v_pk_mul_f32 v[142:143], v[74:75], v[142:143]
	s_nop 0
	v_cvt_pk_bf16_f32 v140, v142, v143
	v_lshlrev_b32_e32 v142, 16, v141
	v_and_b32_e32 v143, 0xffff0000, v141
	v_pk_mul_f32 v[142:143], v[76:77], v[142:143]
	s_nop 0
	v_cvt_pk_bf16_f32 v141, v142, v143
	global_store_dwordx4 v[146:147], v[138:141], off offset:256 sc1
	s_waitcnt vmcnt(7)
	s_nop 0
	v_lshlrev_b32_e32 v140, 16, v134
	v_and_b32_e32 v141, 0xffff0000, v134
	v_pk_mul_f32 v[140:141], v[102:103], v[140:141]
	v_or_b32_e32 v138, 48, v156
	v_cvt_pk_bf16_f32 v134, v140, v141
	v_lshlrev_b32_e32 v140, 16, v135
	v_and_b32_e32 v141, 0xffff0000, v135
	v_pk_mul_f32 v[140:141], v[104:105], v[140:141]
	v_ashrrev_i32_e32 v139, 31, v138
	v_cvt_pk_bf16_f32 v135, v140, v141
	v_lshlrev_b32_e32 v140, 16, v136
	v_and_b32_e32 v141, 0xffff0000, v136
	v_pk_mul_f32 v[140:141], v[98:99], v[140:141]
	v_lshlrev_b64 v[138:139], 12, v[138:139]
	v_cvt_pk_bf16_f32 v136, v140, v141
	v_lshlrev_b32_e32 v140, 16, v137
	v_and_b32_e32 v141, 0xffff0000, v137
	v_pk_mul_f32 v[140:141], v[100:101], v[140:141]
	v_lshl_add_u64 v[138:139], s[12:13], 0, v[138:139]
	v_cvt_pk_bf16_f32 v137, v140, v141
	v_lshl_add_u64 v[138:139], v[138:139], 0, v[158:159]
	global_store_dwordx4 v[138:139], v[134:137], off sc1
	s_waitcnt vmcnt(7)
	s_nop 0
	v_lshlrev_b32_e32 v134, 16, v130
	v_and_b32_e32 v135, 0xffff0000, v130
	v_pk_mul_f32 v[134:135], v[70:71], v[134:135]
	s_nop 0
	v_cvt_pk_bf16_f32 v130, v134, v135
	v_lshlrev_b32_e32 v134, 16, v131
	v_and_b32_e32 v135, 0xffff0000, v131
	v_pk_mul_f32 v[134:135], v[72:73], v[134:135]
	s_nop 0
	v_cvt_pk_bf16_f32 v131, v134, v135
	v_lshlrev_b32_e32 v134, 16, v132
	v_and_b32_e32 v135, 0xffff0000, v132
	v_pk_mul_f32 v[134:135], v[66:67], v[134:135]
	s_nop 0
	v_cvt_pk_bf16_f32 v132, v134, v135
	v_lshlrev_b32_e32 v134, 16, v133
	v_and_b32_e32 v135, 0xffff0000, v133
	v_pk_mul_f32 v[134:135], v[68:69], v[134:135]
	s_nop 0
	v_cvt_pk_bf16_f32 v133, v134, v135
	global_store_dwordx4 v[138:139], v[130:133], off offset:256 sc1
	s_nop 1
	v_add_co_u32_e32 v130, vcc, s0, v214
	s_mov_b32 s0, 0x510000
	s_nop 0
	v_addc_co_u32_e32 v131, vcc, 0, v215, vcc
	global_load_dwordx4 v[134:137], v[130:131], off
	global_load_dwordx4 v[138:141], v[130:131], off offset:256
	v_add_co_u32_e32 v130, vcc, s0, v214
	s_mov_b32 s0, 0x5a0000
	s_nop 0
	v_addc_co_u32_e32 v131, vcc, 0, v215, vcc
	global_load_dwordx4 v[142:145], v[130:131], off
	global_load_dwordx4 v[146:149], v[130:131], off offset:256
	v_add_co_u32_e32 v130, vcc, s0, v214
	s_mov_b32 s0, 0x630000
	s_nop 0
	v_addc_co_u32_e32 v131, vcc, 0, v215, vcc
	global_load_dwordx4 v[150:153], v[130:131], off
	global_load_dwordx4 v[156:159], v[130:131], off offset:256
	v_add_co_u32_e32 v130, vcc, s0, v214
	s_mov_b64 s[0:1], 0x80000
	s_nop 0
	v_addc_co_u32_e32 v131, vcc, 0, v215, vcc
	global_load_dwordx4 v[160:163], v[130:131], off
	s_nop 0
	global_load_dwordx4 v[130:133], v[130:131], off offset:256
	s_waitcnt vmcnt(7)
	v_lshlrev_b32_e32 v164, 16, v134
	v_and_b32_e32 v165, 0xffff0000, v134
	v_pk_mul_f32 v[164:165], v[62:63], v[164:165]
	s_nop 0
	v_cvt_pk_bf16_f32 v134, v164, v165
	v_lshlrev_b32_e32 v164, 16, v135
	v_and_b32_e32 v165, 0xffff0000, v135
	v_pk_mul_f32 v[164:165], v[64:65], v[164:165]
	s_nop 0
	v_cvt_pk_bf16_f32 v135, v164, v165
	v_lshlrev_b32_e32 v164, 16, v136
	v_and_b32_e32 v165, 0xffff0000, v136
	v_pk_mul_f32 v[164:165], v[58:59], v[164:165]
	s_nop 0
	v_cvt_pk_bf16_f32 v136, v164, v165
	v_lshlrev_b32_e32 v164, 16, v137
	v_and_b32_e32 v165, 0xffff0000, v137
	v_pk_mul_f32 v[164:165], v[60:61], v[164:165]
	s_nop 0
	v_cvt_pk_bf16_f32 v137, v164, v165
	v_lshl_add_u64 v[164:165], v[154:155], 0, s[0:1]
	s_mov_b32 s0, 0x80000
	v_add_co_u32_e32 v166, vcc, s0, v154
	s_mov_b64 s[0:1], 0x90000
	s_nop 0
	v_addc_co_u32_e32 v167, vcc, 0, v155, vcc
	global_store_dwordx4 v[166:167], v[134:137], off sc1
	s_waitcnt vmcnt(7)
	s_nop 0
	v_lshlrev_b32_e32 v134, 16, v138
	v_and_b32_e32 v135, 0xffff0000, v138
	v_lshlrev_b32_e32 v136, 16, v139
	v_and_b32_e32 v137, 0xffff0000, v139
	v_pk_mul_f32 v[134:135], v[30:31], v[134:135]
	v_pk_mul_f32 v[136:137], v[32:33], v[136:137]
	v_cvt_pk_bf16_f32 v134, v134, v135
	v_cvt_pk_bf16_f32 v135, v136, v137
	v_lshlrev_b32_e32 v136, 16, v140
	v_and_b32_e32 v137, 0xffff0000, v140
	v_lshlrev_b32_e32 v138, 16, v141
	v_and_b32_e32 v139, 0xffff0000, v141
	v_pk_mul_f32 v[136:137], v[26:27], v[136:137]
	v_pk_mul_f32 v[138:139], v[28:29], v[138:139]
	v_cvt_pk_bf16_f32 v136, v136, v137
	v_cvt_pk_bf16_f32 v137, v138, v139
	global_store_dwordx4 v[164:165], v[134:137], off offset:256 sc1
	s_waitcnt vmcnt(7)
	v_lshlrev_b32_e32 v138, 16, v145
	v_and_b32_e32 v139, 0xffff0000, v145
	v_lshlrev_b32_e32 v134, 16, v142
	v_and_b32_e32 v135, 0xffff0000, v142
	v_lshlrev_b32_e32 v136, 16, v143
	v_and_b32_e32 v137, 0xffff0000, v143
	v_pk_mul_f32 v[134:135], v[54:55], v[134:135]
	v_pk_mul_f32 v[136:137], v[56:57], v[136:137]
	v_cvt_pk_bf16_f32 v134, v134, v135
	v_cvt_pk_bf16_f32 v135, v136, v137
	v_lshlrev_b32_e32 v136, 16, v144
	v_and_b32_e32 v137, 0xffff0000, v144
	v_pk_mul_f32 v[136:137], v[50:51], v[136:137]
	v_pk_mul_f32 v[138:139], v[52:53], v[138:139]
	v_cvt_pk_bf16_f32 v136, v136, v137
	v_cvt_pk_bf16_f32 v137, v138, v139
	v_lshl_add_u64 v[138:139], v[154:155], 0, s[0:1]
	s_mov_b32 s0, 0x90000
	v_add_co_u32_e32 v140, vcc, s0, v154
	s_mov_b64 s[0:1], 0xa0000
	s_nop 0
	v_addc_co_u32_e32 v141, vcc, 0, v155, vcc
	global_store_dwordx4 v[140:141], v[134:137], off sc1
	s_waitcnt vmcnt(7)
	v_lshlrev_b32_e32 v140, 16, v149
	v_and_b32_e32 v141, 0xffff0000, v149
	v_lshlrev_b32_e32 v134, 16, v146
	v_and_b32_e32 v135, 0xffff0000, v146
	v_lshlrev_b32_e32 v136, 16, v147
	v_and_b32_e32 v137, 0xffff0000, v147
	v_pk_mul_f32 v[134:135], v[22:23], v[134:135]
	v_pk_mul_f32 v[136:137], v[24:25], v[136:137]
	v_cvt_pk_bf16_f32 v134, v134, v135
	v_cvt_pk_bf16_f32 v135, v136, v137
	v_lshlrev_b32_e32 v136, 16, v148
	v_and_b32_e32 v137, 0xffff0000, v148
	v_pk_mul_f32 v[136:137], v[18:19], v[136:137]
	v_pk_mul_f32 v[140:141], v[20:21], v[140:141]
	v_cvt_pk_bf16_f32 v136, v136, v137
	v_cvt_pk_bf16_f32 v137, v140, v141
	global_store_dwordx4 v[138:139], v[134:137], off offset:256 sc1
	s_waitcnt vmcnt(7)
	v_lshlrev_b32_e32 v138, 16, v153
	v_and_b32_e32 v139, 0xffff0000, v153
	v_lshlrev_b32_e32 v134, 16, v150
	v_and_b32_e32 v135, 0xffff0000, v150
	v_lshlrev_b32_e32 v136, 16, v151
	v_and_b32_e32 v137, 0xffff0000, v151
	v_pk_mul_f32 v[134:135], v[46:47], v[134:135]
	v_pk_mul_f32 v[136:137], v[48:49], v[136:137]
	v_cvt_pk_bf16_f32 v134, v134, v135
	v_cvt_pk_bf16_f32 v135, v136, v137
	v_lshlrev_b32_e32 v136, 16, v152
	v_and_b32_e32 v137, 0xffff0000, v152
	v_pk_mul_f32 v[136:137], v[42:43], v[136:137]
	v_pk_mul_f32 v[138:139], v[44:45], v[138:139]
	v_cvt_pk_bf16_f32 v136, v136, v137
	v_cvt_pk_bf16_f32 v137, v138, v139
	v_lshl_add_u64 v[138:139], v[154:155], 0, s[0:1]
	s_mov_b32 s0, 0xa0000
	v_add_co_u32_e32 v140, vcc, s0, v154
	s_mov_b64 s[0:1], 0xb0000
	s_nop 0
	v_addc_co_u32_e32 v141, vcc, 0, v155, vcc
	global_store_dwordx4 v[140:141], v[134:137], off sc1
	s_waitcnt vmcnt(7)
	v_lshlrev_b32_e32 v140, 16, v159
	v_and_b32_e32 v141, 0xffff0000, v159
	v_lshlrev_b32_e32 v134, 16, v156
	v_and_b32_e32 v135, 0xffff0000, v156
	v_lshlrev_b32_e32 v136, 16, v157
	v_and_b32_e32 v137, 0xffff0000, v157
	v_pk_mul_f32 v[134:135], v[14:15], v[134:135]
	v_pk_mul_f32 v[136:137], v[16:17], v[136:137]
	v_cvt_pk_bf16_f32 v134, v134, v135
	v_cvt_pk_bf16_f32 v135, v136, v137
	v_lshlrev_b32_e32 v136, 16, v158
	v_and_b32_e32 v137, 0xffff0000, v158
	v_pk_mul_f32 v[136:137], v[10:11], v[136:137]
	v_pk_mul_f32 v[140:141], v[12:13], v[140:141]
	v_cvt_pk_bf16_f32 v136, v136, v137
	v_cvt_pk_bf16_f32 v137, v140, v141
	global_store_dwordx4 v[138:139], v[134:137], off offset:256 sc1
	s_waitcnt vmcnt(7)
	v_lshlrev_b32_e32 v138, 16, v163
	v_and_b32_e32 v139, 0xffff0000, v163
	v_lshlrev_b32_e32 v134, 16, v160
	v_and_b32_e32 v135, 0xffff0000, v160
	v_lshlrev_b32_e32 v136, 16, v161
	v_and_b32_e32 v137, 0xffff0000, v161
	v_pk_mul_f32 v[134:135], v[38:39], v[134:135]
	v_pk_mul_f32 v[136:137], v[40:41], v[136:137]
	v_cvt_pk_bf16_f32 v134, v134, v135
	v_cvt_pk_bf16_f32 v135, v136, v137
	v_lshlrev_b32_e32 v136, 16, v162
	v_and_b32_e32 v137, 0xffff0000, v162
	v_pk_mul_f32 v[136:137], v[34:35], v[136:137]
	v_pk_mul_f32 v[138:139], v[36:37], v[138:139]
	v_cvt_pk_bf16_f32 v136, v136, v137
	v_cvt_pk_bf16_f32 v137, v138, v139
	v_lshl_add_u64 v[138:139], v[154:155], 0, s[0:1]
	s_mov_b32 s0, 0xb0000
	v_add_co_u32_e32 v140, vcc, s0, v154
	s_nop 1
	v_addc_co_u32_e32 v141, vcc, 0, v155, vcc
	global_store_dwordx4 v[140:141], v[134:137], off sc1
	s_waitcnt vmcnt(7)
	s_nop 0
	v_lshlrev_b32_e32 v134, 16, v130
	v_and_b32_e32 v135, 0xffff0000, v130
	v_pk_mul_f32 v[134:135], v[6:7], v[134:135]
	s_nop 0
	v_cvt_pk_bf16_f32 v130, v134, v135
	v_lshlrev_b32_e32 v134, 16, v131
	v_and_b32_e32 v135, 0xffff0000, v131
	v_pk_mul_f32 v[134:135], v[8:9], v[134:135]
	s_nop 0
	v_cvt_pk_bf16_f32 v131, v134, v135
	v_lshlrev_b32_e32 v134, 16, v132
	v_and_b32_e32 v135, 0xffff0000, v132
	v_pk_mul_f32 v[134:135], v[2:3], v[134:135]
	s_nop 0
	v_cvt_pk_bf16_f32 v132, v134, v135
	v_lshlrev_b32_e32 v134, 16, v133
	v_and_b32_e32 v135, 0xffff0000, v133
	v_pk_mul_f32 v[134:135], v[4:5], v[134:135]
	s_nop 0
	v_cvt_pk_bf16_f32 v133, v134, v135
	global_store_dwordx4 v[138:139], v[130:133], off offset:256 sc1
	s_cbranch_execnz .LBB0_501

.LBB0_583:
	s_lshl_b32 s0, s5, 8
	v_readlane_b32 s1, v254, 61
	v_mbcnt_lo_u32_b32 v131, -1, 0
	v_mbcnt_hi_u32_b32 v131, -1, v131
	s_add_i32 s0, s0, s1
	v_and_or_b32 v130, v131, 15, s0
	s_lshl_b32 s0, s4, 8
	v_ashrrev_i32_e32 v131, 1, v131
	v_and_b32_e32 v131, -8, v131
	s_or_b32 s0, s0, s81
	v_add_u32_e32 v132, s0, v131
	v_ashrrev_i32_e32 v133, 31, v132
	v_lshlrev_b64 v[152:153], 2, v[132:133]
	v_ashrrev_i32_e32 v131, 31, v130
	v_lshl_add_u64 v[154:155], s[8:9], 0, v[152:153]
	v_lshlrev_b64 v[156:157], 13, v[130:131]
	v_lshl_add_u64 v[132:133], v[154:155], 0, v[156:157]
	global_load_dwordx4 v[162:165], v[132:133], off offset:16
	global_load_dwordx4 v[166:169], v[132:133], off
	global_load_dwordx4 v[170:173], v[132:133], off offset:528
	global_load_dwordx4 v[174:177], v[132:133], off offset:512
	v_or_b32_e32 v132, 16, v130
	v_ashrrev_i32_e32 v133, 31, v132
	v_lshlrev_b64 v[198:199], 13, v[132:133]
	v_lshl_add_u64 v[132:133], v[154:155], 0, v[198:199]
	global_load_dwordx4 v[178:181], v[132:133], off offset:16
	global_load_dwordx4 v[182:185], v[132:133], off
	global_load_dwordx4 v[186:189], v[132:133], off offset:528
	global_load_dwordx4 v[190:193], v[132:133], off offset:512
	v_or_b32_e32 v132, 32, v130
	v_ashrrev_i32_e32 v133, 31, v132
	v_lshlrev_b64 v[220:221], 13, v[132:133]
	v_or_b32_e32 v130, 48, v130
	v_lshl_add_u64 v[132:133], v[154:155], 0, v[220:221]
	v_ashrrev_i32_e32 v131, 31, v130
	global_load_dwordx4 v[194:197], v[132:133], off offset:16
	global_load_dwordx4 v[204:207], v[132:133], off
	global_load_dwordx4 v[208:211], v[132:133], off offset:528
	global_load_dwordx4 v[212:215], v[132:133], off offset:512
	v_lshlrev_b64 v[158:159], 13, v[130:131]
	v_lshl_add_u64 v[138:139], v[154:155], 0, v[158:159]
	global_load_dwordx4 v[134:137], v[138:139], off offset:16
	global_load_dwordx4 v[216:219], v[138:139], off
	global_load_dwordx4 v[130:133], v[138:139], off offset:528
	s_nop 0
	global_load_dwordx4 v[138:141], v[138:139], off offset:512
	s_mov_b64 s[0:1], 0x100000
	s_andn2_b64 vcc, exec, s[6:7]
	s_waitcnt vmcnt(0)
	v_pk_add_f32 v[124:125], v[124:125], v[164:165]
	v_pk_add_f32 v[126:127], v[126:127], v[166:167]
	v_lshl_add_u64 v[166:167], s[10:11], 0, v[156:157]
	v_lshl_add_u64 v[166:167], v[166:167], 0, v[152:153]
	v_pk_add_f32 v[116:117], v[116:117], v[176:177]
	v_pk_add_f32 v[114:115], v[114:115], v[174:175]
	global_store_dwordx4 v[166:167], v[114:117], off offset:512 sc1
	v_pk_add_f32 v[112:113], v[112:113], v[172:173]
	v_pk_add_f32 v[100:101], v[100:101], v[192:193]
	v_lshl_add_u64 v[114:115], s[10:11], 0, v[198:199]
	v_lshl_add_u64 v[114:115], v[114:115], 0, v[152:153]
	v_pk_add_f32 v[98:99], v[98:99], v[190:191]
	global_store_dwordx4 v[114:115], v[98:101], off offset:512 sc1
	v_pk_add_f32 v[110:111], v[110:111], v[170:171]
	v_pk_add_f32 v[96:97], v[96:97], v[188:189]
	v_lshl_add_u64 v[98:99], s[10:11], 0, v[220:221]
	v_lshl_add_u64 v[98:99], v[98:99], 0, v[152:153]
	v_pk_add_f32 v[84:85], v[84:85], v[214:215]
	v_pk_add_f32 v[82:83], v[82:83], v[212:213]
	v_pk_add_f32 v[94:95], v[94:95], v[186:187]
	global_store_dwordx4 v[98:99], v[82:85], off offset:512 sc1
	v_pk_add_f32 v[80:81], v[80:81], v[210:211]
	v_pk_add_f32 v[78:79], v[78:79], v[208:209]
	v_lshl_add_u64 v[82:83], s[10:11], 0, v[158:159]
	v_pk_add_f32 v[128:129], v[128:129], v[168:169]
	v_pk_add_f32 v[122:123], v[122:123], v[162:163]
	global_store_dwordx4 v[166:167], v[110:113], off offset:528 sc1
	v_pk_add_f32 v[108:109], v[108:109], v[180:181]
	v_pk_add_f32 v[106:107], v[106:107], v[178:179]
	v_pk_add_f32 v[112:113], v[120:121], v[184:185]
	v_pk_add_f32 v[110:111], v[118:119], v[182:183]
	global_store_dwordx4 v[114:115], v[94:97], off offset:528 sc1
	v_pk_add_f32 v[92:93], v[92:93], v[196:197]
	v_pk_add_f32 v[90:91], v[90:91], v[194:195]
	v_pk_add_f32 v[96:97], v[104:105], v[206:207]
	v_pk_add_f32 v[94:95], v[102:103], v[204:205]
	global_store_dwordx4 v[98:99], v[78:81], off offset:528 sc1
	v_lshl_add_u64 v[82:83], v[82:83], 0, v[152:153]
	v_pk_add_f32 v[76:77], v[76:77], v[136:137]
	v_pk_add_f32 v[80:81], v[88:89], v[218:219]
	v_pk_add_f32 v[78:79], v[86:87], v[216:217]
	v_pk_add_f32 v[74:75], v[74:75], v[134:135]
	v_pk_add_f32 v[72:73], v[72:73], v[140:141]
	v_pk_add_f32 v[70:71], v[70:71], v[138:139]
	v_pk_add_f32 v[68:69], v[68:69], v[132:133]
	v_pk_add_f32 v[66:67], v[66:67], v[130:131]
	global_store_dwordx4 v[166:167], v[126:129], off sc1
	global_store_dwordx4 v[166:167], v[122:125], off offset:16 sc1
	global_store_dwordx4 v[114:115], v[110:113], off sc1
	global_store_dwordx4 v[114:115], v[106:109], off offset:16 sc1
	global_store_dwordx4 v[98:99], v[94:97], off sc1
	global_store_dwordx4 v[98:99], v[90:93], off offset:16 sc1
	global_store_dwordx4 v[82:83], v[78:81], off sc1
	global_store_dwordx4 v[82:83], v[74:77], off offset:16 sc1
	global_store_dwordx4 v[82:83], v[70:73], off offset:512 sc1
	global_store_dwordx4 v[82:83], v[66:69], off offset:528 sc1
	v_lshl_add_u64 v[134:135], v[156:157], 0, s[0:1]
	s_mov_b64 s[0:1], 0x120000
	v_lshl_add_u64 v[66:67], v[154:155], 0, v[134:135]
	global_load_dwordx4 v[98:101], v[66:67], off offset:16
	global_load_dwordx4 v[102:105], v[66:67], off
	global_load_dwordx4 v[106:109], v[66:67], off offset:528
	global_load_dwordx4 v[110:113], v[66:67], off offset:512
	v_lshl_add_u64 v[136:137], v[156:157], 0, s[0:1]
	v_lshl_add_u64 v[66:67], v[154:155], 0, v[136:137]
	s_mov_b64 s[0:1], 0x140000
	global_load_dwordx4 v[114:117], v[66:67], off offset:16
	global_load_dwordx4 v[118:121], v[66:67], off
	global_load_dwordx4 v[122:125], v[66:67], off offset:528
	global_load_dwordx4 v[126:129], v[66:67], off offset:512
	v_lshl_add_u64 v[96:97], v[156:157], 0, s[0:1]
	v_lshl_add_u64 v[66:67], v[154:155], 0, v[96:97]
	s_mov_b64 s[0:1], 0x160000
	global_load_dwordx4 v[82:85], v[66:67], off offset:16
	global_load_dwordx4 v[130:133], v[66:67], off
	global_load_dwordx4 v[78:81], v[66:67], off offset:528
	global_load_dwordx4 v[90:93], v[66:67], off offset:512
	v_lshl_add_u64 v[94:95], v[156:157], 0, s[0:1]
	v_lshl_add_u64 v[70:71], v[154:155], 0, v[94:95]
	global_load_dwordx4 v[74:77], v[70:71], off offset:16
	global_load_dwordx4 v[86:89], v[70:71], off
	global_load_dwordx4 v[66:69], v[70:71], off offset:528
	s_nop 0
	global_load_dwordx4 v[70:73], v[70:71], off offset:512
	s_mov_b64 s[0:1], -1
	s_waitcnt vmcnt(15)
	v_pk_add_f32 v[60:61], v[60:61], v[100:101]
	s_waitcnt vmcnt(14)
	v_pk_add_f32 v[62:63], v[62:63], v[102:103]
	v_lshl_add_u64 v[102:103], s[10:11], 0, v[134:135]
	v_lshl_add_u64 v[102:103], v[102:103], 0, v[152:153]
	s_waitcnt vmcnt(12)
	v_pk_add_f32 v[52:53], v[52:53], v[112:113]
	v_pk_add_f32 v[50:51], v[50:51], v[110:111]
	global_store_dwordx4 v[102:103], v[50:53], off offset:512 sc1
	s_waitcnt vmcnt(9)
	v_pk_add_f32 v[36:37], v[36:37], v[128:129]
	v_pk_add_f32 v[34:35], v[34:35], v[126:127]
	v_lshl_add_u64 v[50:51], s[10:11], 0, v[136:137]
	v_lshl_add_u64 v[50:51], v[50:51], 0, v[152:153]
	global_store_dwordx4 v[50:51], v[34:37], off offset:512 sc1
	s_waitcnt vmcnt(6)
	v_pk_add_f32 v[20:21], v[20:21], v[92:93]
	v_pk_add_f32 v[18:19], v[18:19], v[90:91]
	v_lshl_add_u64 v[34:35], s[10:11], 0, v[96:97]
	v_lshl_add_u64 v[34:35], v[34:35], 0, v[152:153]
	v_pk_add_f32 v[48:49], v[48:49], v[108:109]
	v_pk_add_f32 v[46:47], v[46:47], v[106:107]
	v_pk_add_f32 v[32:33], v[32:33], v[124:125]
	v_pk_add_f32 v[30:31], v[30:31], v[122:123]
	global_store_dwordx4 v[34:35], v[18:21], off offset:512 sc1
	v_pk_add_f32 v[16:17], v[16:17], v[80:81]
	v_pk_add_f32 v[14:15], v[14:15], v[78:79]
	v_lshl_add_u64 v[18:19], s[10:11], 0, v[94:95]
	v_pk_add_f32 v[64:65], v[64:65], v[104:105]
	v_pk_add_f32 v[58:59], v[58:59], v[98:99]
	global_store_dwordx4 v[102:103], v[46:49], off offset:528 sc1
	v_pk_add_f32 v[44:45], v[44:45], v[116:117]
	v_pk_add_f32 v[42:43], v[42:43], v[114:115]
	v_pk_add_f32 v[48:49], v[56:57], v[120:121]
	v_pk_add_f32 v[46:47], v[54:55], v[118:119]
	global_store_dwordx4 v[50:51], v[30:33], off offset:528 sc1
	v_pk_add_f32 v[28:29], v[28:29], v[84:85]
	v_pk_add_f32 v[26:27], v[26:27], v[82:83]
	v_pk_add_f32 v[32:33], v[40:41], v[132:133]
	v_pk_add_f32 v[30:31], v[38:39], v[130:131]
	global_store_dwordx4 v[34:35], v[14:17], off offset:528 sc1
	v_lshl_add_u64 v[18:19], v[18:19], 0, v[152:153]
	s_waitcnt vmcnt(9)
	v_pk_add_f32 v[12:13], v[12:13], v[76:77]
	s_waitcnt vmcnt(8)
	v_pk_add_f32 v[16:17], v[24:25], v[88:89]
	v_pk_add_f32 v[14:15], v[22:23], v[86:87]
	v_pk_add_f32 v[10:11], v[10:11], v[74:75]
	s_waitcnt vmcnt(6)
	v_pk_add_f32 v[8:9], v[8:9], v[72:73]
	v_pk_add_f32 v[6:7], v[6:7], v[70:71]
	v_pk_add_f32 v[4:5], v[4:5], v[68:69]
	v_pk_add_f32 v[2:3], v[2:3], v[66:67]
	global_store_dwordx4 v[102:103], v[62:65], off sc1
	global_store_dwordx4 v[102:103], v[58:61], off offset:16 sc1
	global_store_dwordx4 v[50:51], v[46:49], off sc1
	global_store_dwordx4 v[50:51], v[42:45], off offset:16 sc1
	global_store_dwordx4 v[34:35], v[30:33], off sc1
	global_store_dwordx4 v[34:35], v[26:29], off offset:16 sc1
	global_store_dwordx4 v[18:19], v[14:17], off sc1
	global_store_dwordx4 v[18:19], v[10:13], off offset:16 sc1
	global_store_dwordx4 v[18:19], v[6:9], off offset:512 sc1
	global_store_dwordx4 v[18:19], v[2:5], off offset:528 sc1
	s_cbranch_vccnz .LBB0_572
	s_andn2_b64 vcc, exec, s[14:15]
	s_cbranch_vccnz .LBB0_571
	s_barrier
	s_branch .LBB0_571
